# non-temporal hints on the streaming weight-convert loads and stores
# speedup vs baseline: 1.0194x; 1.0092x over previous
; __device__ void phase_convert(PP p, unsigned char* smem) {
;     ...
;     if (tn < NT_ALL) {
;       cvt_decode(p, tn, src2, ld2, dst2, K2, k02, n02, n4);
; #pragma unroll
;       for (int i = 0; i < 4; ++i) nxt[i] = src2 ? *(const f32x4*)(src2 + (size_t)(kl + 16 * i) * ld2) : (f32x4){0.f, 0.f, 0.f, 0.f};
;     }
.Lcvp_body:
	v_lshlrev_b32_e32 v152, 6, v4
	v_mov_b32_e32 v153, 0
	v_lshl_add_u64 v[152:153], v[152:153], 0, v[2:3]
	global_load_dwordx4 v[50:53], v[2:3], off nt
	v_lshl_add_u64 v[2:3], v[2:3], 0, v[4:5]
	global_load_dwordx4 v[54:57], v[2:3], off nt
	v_lshl_add_u64 v[2:3], v[2:3], 0, v[4:5]
	global_load_dwordx4 v[58:61], v[2:3], off nt
	v_lshl_add_u64 v[2:3], v[2:3], 0, v[4:5]
	global_load_dwordx4 v[62:65], v[2:3], off nt
	v_lshl_add_u64 v[2:3], v[2:3], 0, v[4:5]
	global_load_dwordx4 v[66:69], v[2:3], off nt
	v_lshl_add_u64 v[2:3], v[2:3], 0, v[4:5]
	global_load_dwordx4 v[70:73], v[2:3], off nt
	v_lshl_add_u64 v[2:3], v[2:3], 0, v[4:5]
	global_load_dwordx4 v[74:77], v[2:3], off nt
	v_lshl_add_u64 v[2:3], v[2:3], 0, v[4:5]
	global_load_dwordx4 v[78:81], v[2:3], off nt
	global_load_dwordx4 v[82:85], v[152:153], off nt
	v_lshl_add_u64 v[152:153], v[152:153], 0, v[4:5]
	global_load_dwordx4 v[86:89], v[152:153], off nt
	v_lshl_add_u64 v[152:153], v[152:153], 0, v[4:5]
	global_load_dwordx4 v[90:93], v[152:153], off nt
	v_lshl_add_u64 v[152:153], v[152:153], 0, v[4:5]
	global_load_dwordx4 v[94:97], v[152:153], off nt
	v_lshl_add_u64 v[152:153], v[152:153], 0, v[4:5]
	global_load_dwordx4 v[98:101], v[152:153], off nt
	v_lshl_add_u64 v[152:153], v[152:153], 0, v[4:5]
	global_load_dwordx4 v[102:105], v[152:153], off nt
	v_lshl_add_u64 v[152:153], v[152:153], 0, v[4:5]
	global_load_dwordx4 v[106:109], v[152:153], off nt
	v_lshl_add_u64 v[152:153], v[152:153], 0, v[4:5]
	global_load_dwordx4 v[110:113], v[152:153], off nt

; __device__ void phase_convert(PP p, unsigned char* smem) {
;     ...
;       bf16_t* dp = dst + (size_t)(n0 + n) * K + k0 + kg * 16;
;       *(u32x4*)dp = (u32x4){w[0], w[1], w[2], w[3]};
;       *(u32x4*)(dp + 8) = (u32x4){w[4], w[5], w[6], w[7]};
.Lcvp_st:
	global_store_dwordx4 v[6:7], v[114:117], off nt
	global_store_dwordx4 v[6:7], v[118:121], off offset:128 nt
	v_lshl_add_u64 v[6:7], v[6:7], 0, v[8:9]
	global_store_dwordx4 v[6:7], v[122:125], off nt
	global_store_dwordx4 v[6:7], v[126:129], off offset:128 nt
	v_lshl_add_u64 v[6:7], v[6:7], 0, v[8:9]
	global_store_dwordx4 v[6:7], v[130:133], off nt
	global_store_dwordx4 v[6:7], v[134:137], off offset:128 nt
	v_lshl_add_u64 v[6:7], v[6:7], 0, v[8:9]
	global_store_dwordx4 v[6:7], v[138:141], off nt
	global_store_dwordx4 v[6:7], v[142:145], off offset:128 nt
